# v072 variant: two PV MFMAs (with their exp/sum group between) issued before the mid-step barrier; next-step K fragment reads follow the barrier
# baseline (speedup 1.0000x reference)
.Lattn_fx_skipw1:
	v_exp_f32_e32 v78, v78
	v_exp_f32_e32 v79, v79
	v_add_f32_e32 v246, v76, v246
	v_add_f32_e32 v246, v77, v246
	v_cvt_pk_bf16_f32 v71, v76, v77
	v_mfma_f32_32x32x16_bf16 v[98:113], v[186:189], v[138:141], v[98:113]
	v_exp_f32_e32 v80, v80
	v_exp_f32_e32 v81, v81
	v_add_f32_e32 v246, v78, v246
	v_add_f32_e32 v246, v79, v246
	v_cvt_pk_bf16_f32 v72, v78, v79
	v_mfma_f32_32x32x16_bf16 v[114:129], v[174:177], v[142:145], v[114:129]
	v_exp_f32_e32 v34, v34
	v_exp_f32_e32 v35, v35
	v_add_f32_e32 v246, v80, v246
	v_add_f32_e32 v246, v81, v246
	v_cvt_pk_bf16_f32 v73, v80, v81
	v_mfma_f32_32x32x16_bf16 v[98:113], v[82:85], v[142:145], v[98:113]
	v_exp_f32_e32 v36, v36
	v_exp_f32_e32 v37, v37
	v_add_f32_e32 v247, v34, v35
	v_cvt_pk_bf16_f32 v74, v34, v35
	s_waitcnt lgkmcnt(0)
	v_mfma_f32_32x32x16_bf16 v[18:33], v[86:89], v[66:69], v[18:33]
	v_exp_f32_e32 v38, v38
	v_exp_f32_e32 v39, v39
	v_add_f32_e32 v247, v36, v247
	v_add_f32_e32 v247, v37, v247
	v_cvt_pk_bf16_f32 v75, v36, v37
	v_mfma_f32_32x32x16_bf16 v[2:17], v[216:219], v[66:69], v[2:17]
	s_barrier
	ds_read_b128 v[162:165], v193 offset:18432
	ds_read_b128 v[178:181], v193 offset:23040
	v_exp_f32_e32 v40, v40
	v_exp_f32_e32 v41, v41
	v_add_f32_e32 v247, v38, v247
	v_add_f32_e32 v247, v39, v247
	v_cvt_pk_bf16_f32 v76, v38, v39
	v_mfma_f32_32x32x16_bf16 v[18:33], v[90:93], v[70:73], v[18:33]
	ds_read_b128 v[166:169], v193 offset:18464
	ds_read_b128 v[182:185], v193 offset:23072
	v_exp_f32_e32 v42, v42
	v_exp_f32_e32 v43, v43
	v_add_f32_e32 v247, v40, v247
	v_add_f32_e32 v247, v41, v247
	v_cvt_pk_bf16_f32 v77, v40, v41
	v_mfma_f32_32x32x16_bf16 v[2:17], v[220:223], v[70:73], v[2:17]
	ds_read_b128 v[170:173], v193 offset:18496
	ds_read_b128 v[186:189], v193 offset:23104
	v_exp_f32_e32 v44, v44
	v_exp_f32_e32 v45, v45
	v_add_f32_e32 v247, v42, v247
	v_add_f32_e32 v247, v43, v247
	v_cvt_pk_bf16_f32 v78, v42, v43
	v_mfma_f32_32x32x16_bf16 v[18:33], v[94:97], v[74:77], v[18:33]
	ds_read_b128 v[174:177], v193 offset:18528
	ds_read_b128 v[82:85], v193 offset:23136
	v_exp_f32_e32 v46, v46
	v_exp_f32_e32 v47, v47
	v_add_f32_e32 v247, v44, v247
	v_add_f32_e32 v247, v45, v247
	v_cvt_pk_bf16_f32 v79, v44, v45
	v_mfma_f32_32x32x16_bf16 v[2:17], v[224:227], v[74:77], v[2:17]
	v_exp_f32_e32 v48, v48
	v_exp_f32_e32 v49, v49
	v_add_f32_e32 v247, v46, v247
	v_add_f32_e32 v247, v47, v247
	v_cvt_pk_bf16_f32 v80, v46, v47
	v_cvt_pk_bf16_f32 v81, v48, v49
	v_add_f32_e32 v247, v48, v247
	v_add_f32_e32 v247, v49, v247
	v_mfma_f32_32x32x16_bf16 v[18:33], v[212:215], v[78:81], v[18:33]
	v_mfma_f32_32x32x16_bf16 v[2:17], v[242:245], v[78:81], v[2:17]
	v_add_f32_e32 v210, v210, v246
	v_add_f32_e32 v210, v210, v247
	s_min_i32 s24, s10, s58
	s_mul_i32 s44, s24, 0xa0000
	s_add_u32 s44, s3, s44
	s_addc_u32 s45, s12, 0
	s_lshl_b32 s46, s24, 7
	s_add_u32 s46, s15, s46
	s_addc_u32 s47, s23, 0
	global_load_dwordx4 v[146:149], v252, s[44:45] offset:1024
	global_load_dwordx4 v[150:153], v253, s[46:47]
	v_exp_f32_e32 v114, v114
	v_exp_f32_e32 v115, v115
	v_exp_f32_e32 v116, v116
	v_exp_f32_e32 v117, v117
	v_add_f32_e32 v246, v114, v115
	v_cvt_pk_bf16_f32 v114, v114, v115
	s_waitcnt lgkmcnt(0)
	v_mfma_f32_32x32x16_bf16 v[66:81], v[162:165], v[130:133], v[50:65]
	ds_read_b128 v[86:89], v248
	ds_read_b128 v[216:219], v248 offset:4608
	v_exp_f32_e32 v118, v118
	v_exp_f32_e32 v119, v119
	v_add_f32_e32 v246, v116, v246
	v_add_f32_e32 v246, v117, v246
	v_cvt_pk_bf16_f32 v115, v116, v117
	v_mfma_f32_32x32x16_bf16 v[34:49], v[178:181], v[130:133], v[50:65]
	ds_read_b128 v[90:93], v248 offset:32
	ds_read_b128 v[220:223], v248 offset:4640
	v_exp_f32_e32 v120, v120
	v_exp_f32_e32 v121, v121
	v_add_f32_e32 v246, v118, v246
	v_add_f32_e32 v246, v119, v246
	v_cvt_pk_bf16_f32 v116, v118, v119
	v_mfma_f32_32x32x16_bf16 v[66:81], v[166:169], v[134:137], v[66:81]
	ds_read_b128 v[94:97], v248 offset:64
	ds_read_b128 v[224:227], v248 offset:4672
	v_exp_f32_e32 v122, v122
	v_exp_f32_e32 v123, v123
	v_add_f32_e32 v246, v120, v246
	v_add_f32_e32 v246, v121, v246
	v_cvt_pk_bf16_f32 v117, v120, v121
	v_mfma_f32_32x32x16_bf16 v[34:49], v[182:185], v[134:137], v[34:49]
	ds_read_b128 v[212:215], v248 offset:96
	ds_read_b128 v[242:245], v248 offset:4704
	v_exp_f32_e32 v124, v124
	v_exp_f32_e32 v125, v125
	v_add_f32_e32 v246, v122, v246
	v_add_f32_e32 v246, v123, v246
	v_cvt_pk_bf16_f32 v118, v122, v123
	v_mfma_f32_32x32x16_bf16 v[66:81], v[170:173], v[138:141], v[66:81]
	s_cmp_ge_u32 s11, s16
	s_cbranch_scc1 .Lattn_fx_skipw2
	s_waitcnt vmcnt(2)
	ds_write_b128 v192, v[154:157] offset:55296
	ds_write_b128 v204, v[158:161] offset:64512
.Lattn_fx_skipw2:
	v_exp_f32_e32 v126, v126
	v_exp_f32_e32 v127, v127
	v_add_f32_e32 v246, v124, v246
	v_add_f32_e32 v246, v125, v246
	v_cvt_pk_bf16_f32 v119, v124, v125
	v_mfma_f32_32x32x16_bf16 v[34:49], v[186:189], v[138:141], v[34:49]
	v_exp_f32_e32 v128, v128
	v_exp_f32_e32 v129, v129
	v_add_f32_e32 v246, v126, v246
	v_add_f32_e32 v246, v127, v246
	v_cvt_pk_bf16_f32 v120, v126, v127
	v_mfma_f32_32x32x16_bf16 v[66:81], v[174:177], v[142:145], v[66:81]
	v_exp_f32_e32 v98, v98
	v_exp_f32_e32 v99, v99
	v_add_f32_e32 v246, v128, v246
	v_add_f32_e32 v246, v129, v246
	v_cvt_pk_bf16_f32 v121, v128, v129
	v_mfma_f32_32x32x16_bf16 v[34:49], v[82:85], v[142:145], v[34:49]
	v_exp_f32_e32 v100, v100
	v_exp_f32_e32 v101, v101
	v_add_f32_e32 v247, v98, v99
	v_cvt_pk_bf16_f32 v122, v98, v99
	s_waitcnt lgkmcnt(0)
	v_mfma_f32_32x32x16_bf16 v[18:33], v[86:89], v[114:117], v[18:33]
	v_exp_f32_e32 v102, v102
	v_exp_f32_e32 v103, v103
	v_add_f32_e32 v247, v100, v247
	v_add_f32_e32 v247, v101, v247
	v_cvt_pk_bf16_f32 v123, v100, v101
	v_mfma_f32_32x32x16_bf16 v[2:17], v[216:219], v[114:117], v[2:17]
	s_barrier
	ds_read_b128 v[162:165], v193 offset:55296
	ds_read_b128 v[178:181], v193 offset:59904
	v_exp_f32_e32 v104, v104
	v_exp_f32_e32 v105, v105
	v_add_f32_e32 v247, v102, v247
	v_add_f32_e32 v247, v103, v247
	v_cvt_pk_bf16_f32 v124, v102, v103
	v_mfma_f32_32x32x16_bf16 v[18:33], v[90:93], v[118:121], v[18:33]
	ds_read_b128 v[166:169], v193 offset:55328
	ds_read_b128 v[182:185], v193 offset:59936
	v_exp_f32_e32 v106, v106
	v_exp_f32_e32 v107, v107
	v_add_f32_e32 v247, v104, v247
	v_add_f32_e32 v247, v105, v247
	v_cvt_pk_bf16_f32 v125, v104, v105
	v_mfma_f32_32x32x16_bf16 v[2:17], v[220:223], v[118:121], v[2:17]
	ds_read_b128 v[170:173], v193 offset:55360
	ds_read_b128 v[186:189], v193 offset:59968
	v_exp_f32_e32 v108, v108
	v_exp_f32_e32 v109, v109
	v_add_f32_e32 v247, v106, v247
	v_add_f32_e32 v247, v107, v247
	v_cvt_pk_bf16_f32 v126, v106, v107
	v_mfma_f32_32x32x16_bf16 v[18:33], v[94:97], v[122:125], v[18:33]
	ds_read_b128 v[174:177], v193 offset:55392
	ds_read_b128 v[82:85], v193 offset:60000
	v_exp_f32_e32 v110, v110
	v_exp_f32_e32 v111, v111
	v_add_f32_e32 v247, v108, v247
	v_add_f32_e32 v247, v109, v247
	v_cvt_pk_bf16_f32 v127, v108, v109
	v_mfma_f32_32x32x16_bf16 v[2:17], v[224:227], v[122:125], v[2:17]
	v_exp_f32_e32 v112, v112
	v_exp_f32_e32 v113, v113
	v_add_f32_e32 v247, v110, v247
	v_add_f32_e32 v247, v111, v247
	v_cvt_pk_bf16_f32 v128, v110, v111
	v_cvt_pk_bf16_f32 v129, v112, v113
	v_add_f32_e32 v247, v112, v247
	v_add_f32_e32 v247, v113, v247
	v_mfma_f32_32x32x16_bf16 v[18:33], v[212:215], v[126:129], v[18:33]
	v_mfma_f32_32x32x16_bf16 v[2:17], v[242:245], v[126:129], v[2:17]
	v_add_f32_e32 v210, v210, v246
	v_add_f32_e32 v210, v210, v247
	s_add_i32 s10, s10, 2
	s_cmp_lt_u32 s11, s16
	s_cbranch_scc0 .Lattn_fx_exit0
	s_add_i32 s11, s10, -1
	s_min_i32 s1, s11, s58
	s_mul_i32 s44, s1, 0xa0000
	s_add_u32 s44, s3, s44
	s_addc_u32 s45, s12, 0
	s_lshl_b32 s46, s1, 7
	s_add_u32 s46, s15, s46
	s_addc_u32 s47, s23, 0
	s_add_i32 s24, s10, -2
	s_cmp_lt_u32 s24, s16
	s_cselect_b64 s[0:1], -1, 0
	global_load_dwordx4 v[154:157], v252, s[44:45] offset:1024
	global_load_dwordx4 v[158:161], v253, s[46:47]
	v_exp_f32_e32 v66, v66
	v_exp_f32_e32 v67, v67
	v_exp_f32_e32 v68, v68
	v_exp_f32_e32 v69, v69
	v_add_f32_e32 v246, v66, v67
	v_cvt_pk_bf16_f32 v66, v66, v67
	s_waitcnt lgkmcnt(0)
	v_mfma_f32_32x32x16_bf16 v[114:129], v[162:165], v[130:133], v[50:65]
	ds_read_b128 v[86:89], v248 offset:18432
	ds_read_b128 v[216:219], v248 offset:23040
	v_exp_f32_e32 v70, v70
	v_exp_f32_e32 v71, v71
	v_add_f32_e32 v246, v68, v246
	v_add_f32_e32 v246, v69, v246
	v_cvt_pk_bf16_f32 v67, v68, v69
	v_mfma_f32_32x32x16_bf16 v[98:113], v[178:181], v[130:133], v[50:65]
	ds_read_b128 v[90:93], v248 offset:18464
	ds_read_b128 v[220:223], v248 offset:23072
	v_exp_f32_e32 v72, v72
	v_exp_f32_e32 v73, v73
	v_add_f32_e32 v246, v70, v246
	v_add_f32_e32 v246, v71, v246
	v_cvt_pk_bf16_f32 v68, v70, v71
	v_mfma_f32_32x32x16_bf16 v[114:129], v[166:169], v[134:137], v[114:129]
	ds_read_b128 v[94:97], v248 offset:18496
	ds_read_b128 v[224:227], v248 offset:23104
	v_exp_f32_e32 v74, v74
	v_exp_f32_e32 v75, v75
	v_add_f32_e32 v246, v72, v246
	v_add_f32_e32 v246, v73, v246
	v_cvt_pk_bf16_f32 v69, v72, v73
	v_mfma_f32_32x32x16_bf16 v[98:113], v[182:185], v[134:137], v[98:113]
	ds_read_b128 v[212:215], v248 offset:18528
	ds_read_b128 v[242:245], v248 offset:23136
	v_exp_f32_e32 v76, v76
	v_exp_f32_e32 v77, v77
	v_add_f32_e32 v246, v74, v246
	v_add_f32_e32 v246, v75, v246
	v_cvt_pk_bf16_f32 v70, v74, v75
	v_mfma_f32_32x32x16_bf16 v[114:129], v[170:173], v[138:141], v[114:129]
	s_cmp_ge_u32 s24, s16
	s_cbranch_scc1 .Lattn_fx_skipw3
	s_waitcnt vmcnt(2)
	ds_write_b128 v192, v[146:149] offset:36864
	ds_write_b128 v204, v[150:153] offset:46080
.Lattn_fx_skipw3:
	v_exp_f32_e32 v78, v78
	v_exp_f32_e32 v79, v79
	v_add_f32_e32 v246, v76, v246
	v_add_f32_e32 v246, v77, v246
	v_cvt_pk_bf16_f32 v71, v76, v77
	v_mfma_f32_32x32x16_bf16 v[98:113], v[186:189], v[138:141], v[98:113]
	v_exp_f32_e32 v80, v80
	v_exp_f32_e32 v81, v81
	v_add_f32_e32 v246, v78, v246
	v_add_f32_e32 v246, v79, v246
	v_cvt_pk_bf16_f32 v72, v78, v79
	v_mfma_f32_32x32x16_bf16 v[114:129], v[174:177], v[142:145], v[114:129]
	v_exp_f32_e32 v34, v34
	v_exp_f32_e32 v35, v35
	v_add_f32_e32 v246, v80, v246
	v_add_f32_e32 v246, v81, v246
	v_cvt_pk_bf16_f32 v73, v80, v81
	v_mfma_f32_32x32x16_bf16 v[98:113], v[82:85], v[142:145], v[98:113]
	v_exp_f32_e32 v36, v36
	v_exp_f32_e32 v37, v37
	v_add_f32_e32 v247, v34, v35
	v_cvt_pk_bf16_f32 v74, v34, v35
	s_waitcnt lgkmcnt(0)
	v_mfma_f32_32x32x16_bf16 v[18:33], v[86:89], v[66:69], v[18:33]
	v_exp_f32_e32 v38, v38
	v_exp_f32_e32 v39, v39
	v_add_f32_e32 v247, v36, v247
	v_add_f32_e32 v247, v37, v247
	v_cvt_pk_bf16_f32 v75, v36, v37
	v_mfma_f32_32x32x16_bf16 v[2:17], v[216:219], v[66:69], v[2:17]
	s_barrier
	ds_read_b128 v[162:165], v193 offset:36864
	ds_read_b128 v[178:181], v193 offset:41472
	v_exp_f32_e32 v40, v40
	v_exp_f32_e32 v41, v41
	v_add_f32_e32 v247, v38, v247
	v_add_f32_e32 v247, v39, v247
	v_cvt_pk_bf16_f32 v76, v38, v39
	v_mfma_f32_32x32x16_bf16 v[18:33], v[90:93], v[70:73], v[18:33]
	ds_read_b128 v[166:169], v193 offset:36896
	ds_read_b128 v[182:185], v193 offset:41504
	v_exp_f32_e32 v42, v42
	v_exp_f32_e32 v43, v43
	v_add_f32_e32 v247, v40, v247
	v_add_f32_e32 v247, v41, v247
	v_cvt_pk_bf16_f32 v77, v40, v41
	v_mfma_f32_32x32x16_bf16 v[2:17], v[220:223], v[70:73], v[2:17]
	ds_read_b128 v[170:173], v193 offset:36928
	ds_read_b128 v[186:189], v193 offset:41536
	v_exp_f32_e32 v44, v44
	v_exp_f32_e32 v45, v45
	v_add_f32_e32 v247, v42, v247
	v_add_f32_e32 v247, v43, v247
	v_cvt_pk_bf16_f32 v78, v42, v43
	v_mfma_f32_32x32x16_bf16 v[18:33], v[94:97], v[74:77], v[18:33]
	ds_read_b128 v[174:177], v193 offset:36960
	ds_read_b128 v[82:85], v193 offset:41568
	v_exp_f32_e32 v46, v46
	v_exp_f32_e32 v47, v47
	v_add_f32_e32 v247, v44, v247
	v_add_f32_e32 v247, v45, v247
	v_cvt_pk_bf16_f32 v79, v44, v45
	v_mfma_f32_32x32x16_bf16 v[2:17], v[224:227], v[74:77], v[2:17]
	v_exp_f32_e32 v48, v48
	v_exp_f32_e32 v49, v49
	v_add_f32_e32 v247, v46, v247
	v_add_f32_e32 v247, v47, v247
	v_cvt_pk_bf16_f32 v80, v46, v47
	v_cvt_pk_bf16_f32 v81, v48, v49
	v_add_f32_e32 v247, v48, v247
	v_add_f32_e32 v247, v49, v247
	v_mfma_f32_32x32x16_bf16 v[18:33], v[212:215], v[78:81], v[18:33]
	v_mfma_f32_32x32x16_bf16 v[2:17], v[242:245], v[78:81], v[2:17]
	v_add_f32_e32 v210, v210, v246
	v_add_f32_e32 v210, v210, v247
	s_min_i32 s24, s10, s58
	s_mul_i32 s44, s24, 0xa0000
	s_add_u32 s44, s3, s44
	s_addc_u32 s45, s12, 0
	s_lshl_b32 s46, s24, 7
	s_add_u32 s46, s15, s46
	s_addc_u32 s47, s23, 0
	global_load_dwordx4 v[146:149], v252, s[44:45] offset:1024
	global_load_dwordx4 v[150:153], v253, s[46:47]
	v_exp_f32_e32 v114, v114
	v_exp_f32_e32 v115, v115
	v_exp_f32_e32 v116, v116
	v_exp_f32_e32 v117, v117
	v_add_f32_e32 v246, v114, v115
	v_cvt_pk_bf16_f32 v114, v114, v115
	s_waitcnt lgkmcnt(0)
	v_mfma_f32_32x32x16_bf16 v[66:81], v[162:165], v[130:133], v[50:65]
	ds_read_b128 v[86:89], v248 offset:55296
	ds_read_b128 v[216:219], v248 offset:59904
	v_exp_f32_e32 v118, v118
	v_exp_f32_e32 v119, v119
	v_add_f32_e32 v246, v116, v246
	v_add_f32_e32 v246, v117, v246
	v_cvt_pk_bf16_f32 v115, v116, v117
	v_mfma_f32_32x32x16_bf16 v[34:49], v[178:181], v[130:133], v[50:65]
	ds_read_b128 v[90:93], v248 offset:55328
	ds_read_b128 v[220:223], v248 offset:59936
	v_exp_f32_e32 v120, v120
	v_exp_f32_e32 v121, v121
	v_add_f32_e32 v246, v118, v246
	v_add_f32_e32 v246, v119, v246
	v_cvt_pk_bf16_f32 v116, v118, v119
	v_mfma_f32_32x32x16_bf16 v[66:81], v[166:169], v[134:137], v[66:81]
	ds_read_b128 v[94:97], v248 offset:55360
	ds_read_b128 v[224:227], v248 offset:59968
	v_exp_f32_e32 v122, v122
	v_exp_f32_e32 v123, v123
	v_add_f32_e32 v246, v120, v246
	v_add_f32_e32 v246, v121, v246
	v_cvt_pk_bf16_f32 v117, v120, v121
	v_mfma_f32_32x32x16_bf16 v[34:49], v[182:185], v[134:137], v[34:49]
	ds_read_b128 v[212:215], v248 offset:55392
	ds_read_b128 v[242:245], v248 offset:60000
	v_exp_f32_e32 v124, v124
	v_exp_f32_e32 v125, v125
	v_add_f32_e32 v246, v122, v246
	v_add_f32_e32 v246, v123, v246
	v_cvt_pk_bf16_f32 v118, v122, v123
	v_mfma_f32_32x32x16_bf16 v[66:81], v[170:173], v[138:141], v[66:81]
	s_cmp_ge_u32 s11, s16
	s_cbranch_scc1 .Lattn_fx_skipw4
	s_waitcnt vmcnt(2)
	ds_write_b128 v192, v[154:157]
	ds_write_b128 v204, v[158:161] offset:9216
; template <int HD, int MODE> ...
;     ...
;     int t = t0;
;     for (; t + 1 < t1; t += 2) { ATT_STEP(sa0, sa1, sb0, sb1, t, kstB, vstB, kstA, vstA); ATT_STEP(sb0, sb1, sa0, sa1, t + 1, kstA, vstA, kstB, vstB); }
.Lattn_fx_skipw4:
	v_exp_f32_e32 v126, v126
	v_exp_f32_e32 v127, v127
	v_add_f32_e32 v246, v124, v246
	v_add_f32_e32 v246, v125, v246
	v_cvt_pk_bf16_f32 v119, v124, v125
	v_mfma_f32_32x32x16_bf16 v[34:49], v[186:189], v[138:141], v[34:49]
	v_exp_f32_e32 v128, v128
	v_exp_f32_e32 v129, v129
	v_add_f32_e32 v246, v126, v246
	v_add_f32_e32 v246, v127, v246
	v_cvt_pk_bf16_f32 v120, v126, v127
	v_mfma_f32_32x32x16_bf16 v[66:81], v[174:177], v[142:145], v[66:81]
	v_exp_f32_e32 v98, v98
	v_exp_f32_e32 v99, v99
	v_add_f32_e32 v246, v128, v246
	v_add_f32_e32 v246, v129, v246
	v_cvt_pk_bf16_f32 v121, v128, v129
	v_mfma_f32_32x32x16_bf16 v[34:49], v[82:85], v[142:145], v[34:49]
	v_exp_f32_e32 v100, v100
	v_exp_f32_e32 v101, v101
	v_add_f32_e32 v247, v98, v99
	v_cvt_pk_bf16_f32 v122, v98, v99
	s_waitcnt lgkmcnt(0)
	v_mfma_f32_32x32x16_bf16 v[18:33], v[86:89], v[114:117], v[18:33]
	v_exp_f32_e32 v102, v102
	v_exp_f32_e32 v103, v103
	v_add_f32_e32 v247, v100, v247
	v_add_f32_e32 v247, v101, v247
	v_cvt_pk_bf16_f32 v123, v100, v101
	v_mfma_f32_32x32x16_bf16 v[2:17], v[216:219], v[114:117], v[2:17]
	s_barrier
	ds_read_b128 v[162:165], v193
	ds_read_b128 v[178:181], v193 offset:4608
	v_exp_f32_e32 v104, v104
	v_exp_f32_e32 v105, v105
	v_add_f32_e32 v247, v102, v247
	v_add_f32_e32 v247, v103, v247
	v_cvt_pk_bf16_f32 v124, v102, v103
	v_mfma_f32_32x32x16_bf16 v[18:33], v[90:93], v[118:121], v[18:33]
	ds_read_b128 v[166:169], v193 offset:32
	ds_read_b128 v[182:185], v193 offset:4640
	v_exp_f32_e32 v106, v106
	v_exp_f32_e32 v107, v107
	v_add_f32_e32 v247, v104, v247
	v_add_f32_e32 v247, v105, v247
	v_cvt_pk_bf16_f32 v125, v104, v105
	v_mfma_f32_32x32x16_bf16 v[2:17], v[220:223], v[118:121], v[2:17]
	ds_read_b128 v[170:173], v193 offset:64
	ds_read_b128 v[186:189], v193 offset:4672
	v_exp_f32_e32 v108, v108
	v_exp_f32_e32 v109, v109
	v_add_f32_e32 v247, v106, v247
	v_add_f32_e32 v247, v107, v247
	v_cvt_pk_bf16_f32 v126, v106, v107
	v_mfma_f32_32x32x16_bf16 v[18:33], v[94:97], v[122:125], v[18:33]
	ds_read_b128 v[174:177], v193 offset:96
	ds_read_b128 v[82:85], v193 offset:4704
	v_exp_f32_e32 v110, v110
	v_exp_f32_e32 v111, v111
	v_add_f32_e32 v247, v108, v247
	v_add_f32_e32 v247, v109, v247
	v_cvt_pk_bf16_f32 v127, v108, v109
	v_mfma_f32_32x32x16_bf16 v[2:17], v[224:227], v[122:125], v[2:17]
	v_exp_f32_e32 v112, v112
	v_exp_f32_e32 v113, v113
	v_add_f32_e32 v247, v110, v247
	v_add_f32_e32 v247, v111, v247
	v_cvt_pk_bf16_f32 v128, v110, v111
	v_cvt_pk_bf16_f32 v129, v112, v113
	v_add_f32_e32 v247, v112, v247
	v_add_f32_e32 v247, v113, v247
	v_mfma_f32_32x32x16_bf16 v[18:33], v[212:215], v[126:129], v[18:33]
	v_mfma_f32_32x32x16_bf16 v[2:17], v[242:245], v[126:129], v[2:17]
	v_add_f32_e32 v210, v210, v246
	v_add_f32_e32 v210, v210, v247
	s_add_i32 s10, s10, 2
	s_cmp_lt_u32 s11, s16
	s_cbranch_scc0 .Lattn_fx_exit1
	s_branch .Lattn_fx_top
